# MLA attention loop: K/V tile addresses via running pointers; causal-mask index adds moved inside the diagonal-only block
# speedup vs baseline: 1.0049x; 1.0049x over previous
;     ...
;     u32x4 kreg[NKC], vreg[NVC];
;     auto gload = [&](int kt) {
; #pragma unroll
;         for (int i = 0; i < NKC; ++i) { const int c = tid + i * NTHR; if (c < 64 * KCH) { const int row = c / KCH, col = (c % KCH) * 8;
;             kreg[i] = col < D1 ? *(const u32x4*)(K1 + (size_t)(kt * 64 + row) * ldk1 + col) : *(const u32x4*)(K2 + (size_t)(kt * 64 + row) * ldk2 + (col - D1)); } }
; #pragma unroll
;         for (int i = 0; i < NVC; ++i) { const int c = tid + i * NTHR, d = c >> 3, ch = c & 7; vreg[i] = *(const u32x4*)(Vt + (size_t)d * ldvt + kt * 64 + ch * 8); }
;     };
;     auto sstore = [&](int buf) {
; #pragma unroll
;         for (int i = 0; i < NKC; ++i) { const int c = tid + i * NTHR; if (c < 64 * KCH) { const int row = c / KCH, col = (c % KCH) * 8; *(u32x4*)(sK + buf * STG + row * LDK + col) = kreg[i]; } }
; #pragma unroll
;         for (int i = 0; i < NVC; ++i) { const int c = tid + i * NTHR, d = c >> 3, ch = c & 7; *(u32x4*)(sV + buf * STG + d * LDV + ch * 8) = vreg[i]; }
;     };
;     gload(0);
;     __syncthreads();
;     sstore(0);
;     if (nkt > 1) gload(1);
;     __syncthreads();
;     int slot = 0;
.LBB0_695:
	s_or_b64 exec, exec, s[2:3]
	global_load_dwordx4 v[96:99], v[122:123], off offset:128
	v_add_u32_e32 v10, v11, v10
	v_mul_lo_u32 v0, v10, 12
	v_sub_u32_e32 v8, v8, v0
	s_movk_i32 s3, 0xe0
	v_add_u32_e32 v140, s10, v9
	v_lshlrev_b32_e32 v0, 3, v8
	v_mul_lo_u32 v2, v10, s3
	v_lshlrev_b32_e32 v3, 4, v8
	v_mul_lo_u32 v9, v4, s3
	v_lshlrev_b32_e32 v11, 1, v160
	s_ashr_i32 s2, s18, 6
	v_ashrrev_i32_e32 v1, 31, v0
	v_add3_u32 v144, 0, v2, v3
	v_ashrrev_i32_e32 v3, 31, v160
	v_mov_b32_e32 v2, v160
	v_add3_u32 v146, 0, v9, v11
	v_cmp_gt_i32_e64 s[42:43], 8, v8
	v_mov_b32_e32 v8, v0
	v_mov_b32_e32 v9, v161
	v_mul_u32_u24_e32 v135, 0x90, v6
	v_mov_b32_e32 v24, v161
	v_mov_b32_e32 v25, v161
	v_mov_b32_e32 v26, v161
	v_mov_b32_e32 v27, v161
	s_and_b32 s2, s2, -4
	v_lshl_add_u64 v[124:125], v[8:9], 1, s[28:29]
	v_lshl_add_u64 v[126:127], v[0:1], 1, s[0:1]
	v_cmp_gt_i32_e64 s[44:45], 8, v5
	v_lshl_add_u64 v[128:129], v[160:161], 1, s[28:29]
	v_lshl_add_u64 v[130:131], v[2:3], 1, s[0:1]
	v_lshl_add_u32 v143, v12, 1, 0
	v_or_b32_e32 v136, v140, v6
	v_lshlrev_b32_e32 v134, 2, v7
	v_mul_u32_u24_e32 v145, 0x70, v6
	v_add3_u32 v148, 0, v135, v12
	v_add_u32_e32 v149, 0x80, v10
	v_add_u32_e32 v150, 0x80, v4
	v_mov_b32_e32 v165, v164
	v_mov_b32_e32 v160, v161
	v_mov_b64_e32 v[0:1], v[24:25]
	v_mov_b64_e32 v[8:9], v[24:25]
	v_mov_b64_e32 v[30:31], v[26:27]
	v_mov_b64_e32 v[16:17], v[24:25]
	v_mov_b64_e32 v[4:5], v[24:25]
	v_mov_b64_e32 v[12:13], v[24:25]
	v_mov_b64_e32 v[20:21], v[24:25]
	s_sub_i32 s5, 32, s2
	v_or_b32_e32 v142, 31, v140
	s_movk_i32 s77, 0xe0
	v_or_b32_e32 v139, 16, v136
	v_add_u32_e32 v138, 14, v136
	v_add_u32_e32 v137, 13, v136
	v_lshl_add_u32 v147, v145, 1, v143
	s_sub_i32 s28, 31, s2
	s_mov_b32 s29, 0
	v_mov_b64_e32 v[2:3], v[26:27]
	v_mov_b64_e32 v[10:11], v[26:27]
	v_mov_b64_e32 v[28:29], v[24:25]
	v_mov_b64_e32 v[18:19], v[26:27]
	v_mov_b64_e32 v[6:7], v[26:27]
	v_mov_b64_e32 v[14:15], v[26:27]
	v_mov_b64_e32 v[22:23], v[26:27]
	s_mov_b32 s2, 0
	s_mov_b32 s56, 0
	v_mov_b64_e32 v[120:121], v[160:161]
	v_mov_b64_e32 v[100:101], v[164:165]
	s_waitcnt lgkmcnt(0)
	s_barrier
	v_mov_b32_e32 v218, v149
	v_ashrrev_i32_e32 v219, 31, v149
	v_lshlrev_b64 v[220:221], 10, v[218:219]
	v_lshlrev_b64 v[218:219], 6, v[218:219]
	v_lshl_add_u64 v[218:219], v[124:125], 0, v[218:219]
	v_lshl_add_u64 v[220:221], v[126:127], 0, v[220:221]
	v_lshl_add_u64 v[218:219], v[218:219], 0, s[60:61]
	v_cndmask_b32_e64 v219, v219, v221, s[42:43]
	v_cndmask_b32_e64 v218, v218, v220, s[42:43]
	v_mov_b32_e32 v220, 0x1000
	v_mov_b32_e32 v221, 0x10000
	v_cndmask_b32_e64 v220, v220, v221, s[42:43]
	v_mov_b32_e32 v221, 0
	v_mov_b32_e32 v222, v150
	v_ashrrev_i32_e32 v223, 31, v150
	v_lshlrev_b64 v[224:225], 10, v[222:223]
	v_lshlrev_b64 v[222:223], 6, v[222:223]
	v_lshl_add_u64 v[222:223], v[128:129], 0, v[222:223]
	v_lshl_add_u64 v[224:225], v[130:131], 0, v[224:225]
	v_lshl_add_u64 v[222:223], v[222:223], 0, s[60:61]
	v_cndmask_b32_e64 v223, v223, v225, s[44:45]
	v_cndmask_b32_e64 v222, v222, v224, s[44:45]
	v_mov_b32_e32 v224, 0x1000
	v_mov_b32_e32 v225, 0x10000
	v_cndmask_b32_e64 v224, v224, v225, s[44:45]
	v_mov_b32_e32 v225, 0
	s_mov_b64 s[0:1], 0x100
	v_lshl_add_u64 v[226:227], s[0:1], 0, v[122:123]

;     ...
;     auto gload = [&](int kt) {
; #pragma unroll
;         for (int i = 0; i < NKC; ++i) { const int c = tid + i * NTHR; if (c < 64 * KCH) { const int row = c / KCH, col = (c % KCH) * 8;
;             kreg[i] = col < D1 ? *(const u32x4*)(K1 + (size_t)(kt * 64 + row) * ldk1 + col) : *(const u32x4*)(K2 + (size_t)(kt * 64 + row) * ldk2 + (col - D1)); } }
; #pragma unroll
;         for (int i = 0; i < NVC; ++i) { const int c = tid + i * NTHR, d = c >> 3, ch = c & 7; vreg[i] = *(const u32x4*)(Vt + (size_t)d * ldvt + kt * 64 + ch * 8); }
;     };
;     ...
;         if (kt + 1 < nkt) { sstore(nslot); if (kt + 2 < nkt) gload(kt + 2); }
.LBB0_700:
	s_or_b64 exec, exec, s[0:1]
	s_add_i32 s0, s56, 2
	v_lshl_add_u32 v102, s4, 1, v141
	s_cmp_ge_u32 s0, s5
	s_waitcnt vmcnt(0)
	ds_write_b128 v102, v[96:99] offset:14336
	s_cbranch_scc1 .LBB0_706
	s_and_saveexec_b64 s[0:1], s[38:39]
	s_cbranch_execz .LBB0_703
	global_load_dwordx4 v[80:83], v[218:219], off
	v_lshl_add_u64 v[218:219], v[220:221], 0, v[218:219]
.LBB0_703:
	s_or_b64 exec, exec, s[0:1]
	s_and_saveexec_b64 s[0:1], s[40:41]
	s_cbranch_execz .LBB0_705
	global_load_dwordx4 v[88:91], v[222:223], off
	v_lshl_add_u64 v[222:223], v[224:225], 0, v[222:223]
.LBB0_705:
	s_or_b64 exec, exec, s[0:1]
	global_load_dwordx4 v[96:99], v[226:227], off
	s_mov_b64 s[0:1], 0x80
	v_lshl_add_u64 v[226:227], s[0:1], 0, v[226:227]

;     ...
;             if (CAUSAL && kt * 64 + 63 > q0 + w * 16 * MIA) {
;                 const int qabs = q0 + w * 16 * MIA + mi * 16 + fr;
; #pragma unroll
;                 for (int ni = 0; ni < 4; ++ni)
; #pragma unroll
;                     for (int r = 0; r < 4; ++r) { const int kabs = kt * 64 + ni * 16 + fq * 4 + r; if (kabs > qabs) s[mi][ni][r] = -1e30f; }
;             }
.LBB0_708:
	s_or_b64 exec, exec, s[0:1]
	s_waitcnt lgkmcnt(0)
	s_barrier
	s_and_saveexec_b64 s[2:3], vcc
	s_cbranch_execz .LBB0_718
	s_add_i32 s0, s29, 63
	v_cmp_gt_i32_e64 s[46:47], s0, v140
	s_and_saveexec_b64 s[0:1], s[46:47]
	s_cbranch_execz .LBB0_711
	v_add_u32_e32 v114, s29, v134
	v_add_u32_e32 v113, 2, v114
	v_add_u32_e32 v112, 3, v114
	v_add_u32_e32 v111, 16, v114
	v_add_u32_e32 v110, 17, v114
	v_add_u32_e32 v109, 18, v114
	v_add_u32_e32 v108, 19, v114
	v_add_u32_e32 v107, 32, v114
	v_add_u32_e32 v106, 33, v114
	v_add_u32_e32 v105, 34, v114
	v_add_u32_e32 v104, 35, v114
	v_mov_b32_e32 v102, s17
	v_cmp_gt_i32_e32 vcc, v114, v136
	v_add_u32_e32 v103, 48, v114
	s_nop 0
	v_cndmask_b32_e32 v102, v76, v102, vcc
	v_cmp_lt_i32_e32 vcc, v114, v136
	s_nop 1
	v_cndmask_b32_e32 v76, v102, v76, vcc
	v_cndmask_b32_e32 v77, v164, v77, vcc
	v_cmp_le_i32_e32 vcc, v113, v136
	v_mov_b32_e32 v102, s17
	s_nop 0
	v_cndmask_b32_e32 v78, v164, v78, vcc
	v_cmp_le_i32_e32 vcc, v112, v136
	s_nop 1
	v_cndmask_b32_e32 v79, v164, v79, vcc
	v_cmp_gt_i32_e32 vcc, v111, v136
	s_nop 1
	v_cndmask_b32_e32 v72, v72, v102, vcc
	v_cmp_le_i32_e32 vcc, v110, v136
	s_nop 1
	v_cndmask_b32_e32 v73, v164, v73, vcc
	v_cmp_le_i32_e32 vcc, v109, v136
	s_nop 1
	v_cndmask_b32_e32 v74, v164, v74, vcc
	v_cmp_le_i32_e32 vcc, v108, v136
	s_nop 1
	v_cndmask_b32_e32 v75, v164, v75, vcc
	v_cmp_gt_i32_e32 vcc, v107, v136
	s_nop 1
	v_cndmask_b32_e32 v84, v84, v102, vcc
	v_cmp_le_i32_e32 vcc, v106, v136
	s_nop 1
	v_cndmask_b32_e32 v85, v164, v85, vcc
	v_cmp_le_i32_e32 vcc, v105, v136
	s_nop 1
	v_cndmask_b32_e32 v86, v164, v86, vcc
	v_cmp_le_i32_e32 vcc, v104, v136
	s_nop 1
	v_cndmask_b32_e32 v87, v164, v87, vcc
	v_cmp_gt_i32_e32 vcc, v103, v136
	s_nop 1
	v_cndmask_b32_e32 v92, v92, v102, vcc
	v_add_u32_e32 v102, 49, v114
	v_cmp_le_i32_e32 vcc, v102, v136
	v_add_u32_e32 v102, 50, v114
	s_nop 0
	v_cndmask_b32_e32 v93, v164, v93, vcc
	v_cmp_le_i32_e32 vcc, v102, v136
	v_add_u32_e32 v102, 51, v114
	s_nop 0
	v_cndmask_b32_e32 v94, v164, v94, vcc
	v_cmp_le_i32_e32 vcc, v102, v136
	s_nop 1
	v_cndmask_b32_e32 v95, v164, v95, vcc
